# S3 pointwise-conv GEMM unit: first K iteration peeled (SrcC=0), 128 accumulator-zeroing movs removed
# speedup vs baseline: 1.0036x; 1.0011x over previous
; #define PG8_STAGE(bufoff, gbase, voff) do { _Pragma("unroll") for (int _i = 0; _i < 2; ++_i) \
;         __builtin_amdgcn_global_load_lds((const unsigned*)((const char*)(gbase) + (voff)[_i]), (PG8_LAS unsigned*)(lds + (bufoff) + ldsw + _i * 8192), 16, 0, 0); } while (0)
; #define PG8_LDA(dst, b, h) do { _Pragma("unroll") for (int m = 0; m < 4; ++m) _Pragma("unroll") for (int k = 0; k < 2; ++k) dst[m][k] = *(const PG8_LAS bf16x8*)(lds + PG8_SA(b, h) + aoff + m * 2048 + k * 1024); } while (0)
; #define PG8_LDB(dst, b, h) do { _Pragma("unroll") for (int n = 0; n < 2; ++n) _Pragma("unroll") for (int k = 0; k < 2; ++k) dst[n][k] = *(const PG8_LAS bf16x8*)(lds + PG8_SB(b, h) + boff + n * 2048 + k * 1024); } while (0)
; #define PG8_WAIT_V(n) asm volatile("s_waitcnt vmcnt(" #n ")" ::: "memory")
; #define PG8_WAIT_L(n) asm volatile("s_waitcnt lgkmcnt(" #n ")" ::: "memory")
; #define PG8_BAR __builtin_amdgcn_s_barrier()
; template <class Epi, class Sched, bool ALIGN_EPI = false, bool SP2 = false>
; __device__ __forceinline__ void gemm_phase(PG8_LAS unsigned char* lds, const Gemm g, const Sched& S, const Epi& E) {
;     ...
;         for (int t = 0; t < nt; t += 2) {
;             const bool last = (t == nt - 2);
;             const char* a1 = cA + (size_t)(t + 1) * kstep;
;             const char* a2 = last ? nA : cA + (size_t)(t + 2) * kstep; const char* b2 = last ? nB : cB + (size_t)(t + 2) * kstep;
;             const char* a3 = a2 + kstep; const char* b3 = b2 + kstep;
;             if (last && has_next) S.a_ready(nxt);
;             if constexpr (SP2) {
;             PG8_LDB(B0, 0, 0); PG8_LDB(B1, 0, 1); PG8_SCHED; PG8_LDA(At, 0, 0); PG8_STAGE(PG8_SA(1, 1), a1 + hstep, voffA);
;             PG8_WAIT_V(8); PG8_WAIT_L(0); PG8_BAR; PG8_MMA(0, 0, At, B0); PG8_MMA(0, 1, At, B1); PG8_BAR; PG8_SCHED;
;             PG8_LDA(At, 0, 1); PG8_STAGE(PG8_SB(0, 0), b2, voffB); PG8_STAGE(PG8_SB(0, 1), b2 + hstep, voffB); PG8_STAGE(PG8_SA(0, 0), a2, voffA);
;             PG8_WAIT_V(8); PG8_WAIT_L(0); PG8_BAR; PG8_MMA(1, 0, At, B0); PG8_MMA(1, 1, At, B1); PG8_BAR; PG8_SCHED;
;     ...
; #pragma unroll
;         for (int a = 0; a < 2; ++a)
; #pragma unroll
;             for (int b = 0; b < 2; ++b)
; #pragma unroll
;                 for (int m = 0; m < 4; ++m)
; #pragma unroll
;                     for (int n = 0; n < 2; ++n) acc[a][b][m][n] = (f32x4){0.f, 0.f, 0.f, 0.f};
.LBB0_744:
	s_ashr_i32 s9, s8, 31
	s_lshl_b64 s[12:13], s[8:9], 18
	v_readlane_b32 s16, v253, 31
	v_readlane_b32 s17, v253, 32
	s_add_u32 s12, s16, s12
	s_addc_u32 s13, s17, s13
	s_and_b64 s[16:17], s[14:15], exec
	s_cselect_b32 s9, s13, s1
	s_cselect_b32 s35, s12, s0
	s_ashr_i32 s11, s10, 31
	s_lshl_b64 s[16:17], s[10:11], 18
	s_add_u32 s16, s23, s16
	s_addc_u32 s17, s24, s17
	s_and_b64 s[20:21], s[14:15], exec
	s_cselect_b32 s11, s17, s19
	s_cselect_b32 s36, s16, s18
	s_add_u32 s0, s0, 0x20080
	s_addc_u32 s1, s1, 0
	s_add_u32 s37, s18, 0x100
	s_addc_u32 s38, s19, 0
	s_mov_b32 s39, -2
	s_add_u32 s18, s0, 0xfffe0080
	s_addc_u32 s19, s1, -1
	s_add_i32 s40, 0, 0x10000
	s_cmp_eq_u32 s39, 4
	s_cselect_b32 s21, s9, s19
	s_cselect_b32 s20, s35, s18
	s_cselect_b32 s19, s11, s38
	s_cselect_b32 s18, s36, s37
	s_add_i32 s42, 0, 0x14000
	v_add_u32_e32 v142, s40, v161
	v_add_u32_e32 v177, s42, v161
	ds_read_b128 v[130:133], v142
	ds_read_b128 v[134:137], v142 offset:1024
	ds_read_b128 v[138:141], v142 offset:2048
	ds_read_b128 v[142:145], v142 offset:3072
	ds_read_b128 v[156:159], v177
	ds_read_b128 v[164:167], v177 offset:1024
	ds_read_b128 v[172:175], v177 offset:2048
	ds_read_b128 v[178:181], v177 offset:3072
	v_lshl_add_u64 v[228:229], s[0:1], 0, v[152:153]
	s_add_i32 m0, s25, 0xc000
	ds_read_b128 v[182:185], v176
	ds_read_b128 v[200:203], v176 offset:1024
	ds_read_b128 v[204:207], v176 offset:2048
	ds_read_b128 v[208:211], v176 offset:3072
	ds_read_b128 v[212:215], v176 offset:4096
	ds_read_b128 v[216:219], v176 offset:5120
	ds_read_b128 v[220:223], v176 offset:6144
	ds_read_b128 v[224:227], v176 offset:7168
	global_load_lds_dwordx4 v[228:229], off
	v_lshl_add_u64 v[228:229], s[0:1], 0, v[154:155]
	s_add_i32 m0, s25, 0xe000
	s_nop 0
	global_load_lds_dwordx4 v[228:229], off
	s_waitcnt vmcnt(8)
	s_waitcnt lgkmcnt(0)
	s_barrier
	s_setprio 1
	s_waitcnt lgkmcnt(0)
	v_mfma_f32_16x16x32_bf16 v[126:129], v[130:133], v[182:185], 0
	v_mfma_f32_16x16x32_bf16 v[122:125], v[138:141], v[182:185], 0
	v_mfma_f32_16x16x32_bf16 v[114:117], v[130:133], v[204:207], 0
	v_mfma_f32_16x16x32_bf16 v[106:109], v[138:141], v[204:207], 0
	v_mfma_f32_16x16x32_bf16 v[98:101], v[130:133], v[212:215], 0
	v_mfma_f32_16x16x32_bf16 v[90:93], v[138:141], v[212:215], 0
	v_mfma_f32_16x16x32_bf16 v[82:85], v[130:133], v[220:223], 0
	v_mfma_f32_16x16x32_bf16 v[74:77], v[138:141], v[220:223], 0
	v_mfma_f32_16x16x32_bf16 v[126:129], v[134:137], v[200:203], v[126:129]
	v_mfma_f32_16x16x32_bf16 v[122:125], v[142:145], v[200:203], v[122:125]
	v_mfma_f32_16x16x32_bf16 v[114:117], v[134:137], v[208:211], v[114:117]
	v_mfma_f32_16x16x32_bf16 v[106:109], v[142:145], v[208:211], v[106:109]
	v_mfma_f32_16x16x32_bf16 v[98:101], v[134:137], v[216:219], v[98:101]
	v_mfma_f32_16x16x32_bf16 v[90:93], v[142:145], v[216:219], v[90:93]
	v_mfma_f32_16x16x32_bf16 v[82:85], v[134:137], v[224:227], v[82:85]
	v_mfma_f32_16x16x32_bf16 v[74:77], v[142:145], v[224:227], v[74:77]
	s_setprio 0
	s_setprio 1
	v_mfma_f32_16x16x32_bf16 v[118:121], v[156:159], v[182:185], 0
	v_mfma_f32_16x16x32_bf16 v[110:113], v[172:175], v[182:185], 0
	v_mfma_f32_16x16x32_bf16 v[102:105], v[156:159], v[204:207], 0
	v_mfma_f32_16x16x32_bf16 v[94:97], v[172:175], v[204:207], 0
	v_mfma_f32_16x16x32_bf16 v[86:89], v[156:159], v[212:215], 0
	v_mfma_f32_16x16x32_bf16 v[78:81], v[172:175], v[212:215], 0
	v_mfma_f32_16x16x32_bf16 v[70:73], v[156:159], v[220:223], 0
	v_mfma_f32_16x16x32_bf16 v[66:69], v[172:175], v[220:223], 0
	v_mfma_f32_16x16x32_bf16 v[118:121], v[164:167], v[200:203], v[118:121]
	v_mfma_f32_16x16x32_bf16 v[110:113], v[178:181], v[200:203], v[110:113]
	v_mfma_f32_16x16x32_bf16 v[102:105], v[164:167], v[208:211], v[102:105]
	v_mfma_f32_16x16x32_bf16 v[94:97], v[178:181], v[208:211], v[94:97]
	v_mfma_f32_16x16x32_bf16 v[86:89], v[164:167], v[216:219], v[86:89]
	v_mfma_f32_16x16x32_bf16 v[78:81], v[178:181], v[216:219], v[78:81]
	v_mfma_f32_16x16x32_bf16 v[70:73], v[164:167], v[224:227], v[70:73]
	v_mfma_f32_16x16x32_bf16 v[66:69], v[178:181], v[224:227], v[66:69]
	s_setprio 0
	s_barrier
	s_add_i32 s40, s40, s22
	v_lshl_add_u64 v[228:229], s[18:19], 0, v[0:1]
	s_mov_b32 m0, s40
	ds_read_b128 v[182:185], v176 offset:16384
	ds_read_b128 v[200:203], v176 offset:17408
	ds_read_b128 v[204:207], v176 offset:18432
	ds_read_b128 v[208:211], v176 offset:19456
	ds_read_b128 v[212:215], v176 offset:20480
	ds_read_b128 v[216:219], v176 offset:21504
	ds_read_b128 v[220:223], v176 offset:22528
	ds_read_b128 v[224:227], v176 offset:23552
	global_load_lds_dwordx4 v[228:229], off
	s_add_i32 m0, s40, 0x2000
	s_add_u32 s40, s18, 0x20000
	v_lshl_add_u64 v[230:231], s[18:19], 0, v[146:147]
	s_addc_u32 s41, s19, 0
	s_add_i32 s42, s42, s22
	global_load_lds_dwordx4 v[230:231], off
	v_lshl_add_u64 v[232:233], s[40:41], 0, v[0:1]
	s_mov_b32 m0, s42
	v_lshl_add_u64 v[234:235], s[20:21], 0, v[148:149]
	global_load_lds_dwordx4 v[232:233], off
	v_lshl_add_u64 v[232:233], s[40:41], 0, v[146:147]
	s_add_i32 m0, s42, 0x2000
	s_nop 0
	global_load_lds_dwordx4 v[232:233], off
	v_lshl_add_u64 v[232:233], s[20:21], 0, v[150:151]
	s_mov_b32 m0, s25
	s_nop 0
	global_load_lds_dwordx4 v[232:233], off
	s_mov_b32 m0, s26
	s_nop 0
	global_load_lds_dwordx4 v[234:235], off
	s_waitcnt vmcnt(8)
	s_waitcnt lgkmcnt(0)
	s_barrier
; #define PG8_STAGE(bufoff, gbase, voff) do { _Pragma("unroll") for (int _i = 0; _i < 2; ++_i) \
;         __builtin_amdgcn_global_load_lds((const unsigned*)((const char*)(gbase) + (voff)[_i]), (PG8_LAS unsigned*)(lds + (bufoff) + ldsw + _i * 8192), 16, 0, 0); } while (0)
; #define PG8_LDA(dst, b, h) do { _Pragma("unroll") for (int m = 0; m < 4; ++m) _Pragma("unroll") for (int k = 0; k < 2; ++k) dst[m][k] = *(const PG8_LAS bf16x8*)(lds + PG8_SA(b, h) + aoff + m * 2048 + k * 1024); } while (0)
; #define PG8_LDB(dst, b, h) do { _Pragma("unroll") for (int n = 0; n < 2; ++n) _Pragma("unroll") for (int k = 0; k < 2; ++k) dst[n][k] = *(const PG8_LAS bf16x8*)(lds + PG8_SB(b, h) + boff + n * 2048 + k * 1024); } while (0)
; #define PG8_MMA(ai, bj, At, Bt) do { __builtin_amdgcn_s_setprio(1); _Pragma("unroll") for (int m = 0; m < 4; ++m) _Pragma("unroll") for (int n = 0; n < 2; ++n) _Pragma("unroll") for (int k = 0; k < 2; ++k) \
;         acc[ai][bj][m][n] = __builtin_amdgcn_mfma_f32_16x16x32_bf16(Bt[n][k], At[m][k], acc[ai][bj][m][n], 0, 0, 0); __builtin_amdgcn_s_setprio(0); } while (0)
; #define PG8_WAIT_V(n) asm volatile("s_waitcnt vmcnt(" #n ")" ::: "memory")
; #define PG8_WAIT_L(n) asm volatile("s_waitcnt lgkmcnt(" #n ")" ::: "memory")
; #define PG8_BAR __builtin_amdgcn_s_barrier()
; #define PG8_SCHED __builtin_amdgcn_sched_barrier(0)
; template <class Epi, class Sched, bool ALIGN_EPI = false, bool SP2 = false>
; __device__ __forceinline__ void gemm_phase(PG8_LAS unsigned char* lds, const Gemm g, const Sched& S, const Epi& E) {
;     ...
;             PG8_LDA(At, 0, 1); PG8_STAGE(PG8_SB(0, 0), b2, voffB); PG8_STAGE(PG8_SB(0, 1), b2 + hstep, voffB); PG8_STAGE(PG8_SA(0, 0), a2, voffA);
;             PG8_WAIT_V(8); PG8_WAIT_L(0); PG8_BAR; PG8_MMA(1, 0, At, B0); PG8_MMA(1, 1, At, B1); PG8_BAR; PG8_SCHED;
;             PG8_LDB(B0, 1, 0); PG8_LDB(B1, 1, 1); PG8_SCHED; PG8_LDA(At, 1, 0); PG8_STAGE(PG8_SA(0, 1), a2 + hstep, voffA);
;             PG8_WAIT_V(8); PG8_WAIT_L(0); PG8_BAR; PG8_MMA(0, 0, At, B0); PG8_MMA(0, 1, At, B1); PG8_BAR; PG8_SCHED;
;             PG8_LDA(At, 1, 1); PG8_STAGE(PG8_SB(1, 0), b3, voffB); PG8_STAGE(PG8_SB(1, 1), b3 + hstep, voffB); PG8_STAGE(PG8_SA(1, 0), a3, voffA);
	s_setprio 1
	s_waitcnt lgkmcnt(0)
	v_mfma_f32_16x16x32_bf16 v[62:65], v[130:133], v[182:185], 0
	v_mfma_f32_16x16x32_bf16 v[58:61], v[138:141], v[182:185], 0
	v_mfma_f32_16x16x32_bf16 v[50:53], v[130:133], v[204:207], 0
	v_mfma_f32_16x16x32_bf16 v[42:45], v[138:141], v[204:207], 0
	v_mfma_f32_16x16x32_bf16 v[34:37], v[130:133], v[212:215], 0
	v_mfma_f32_16x16x32_bf16 v[26:29], v[138:141], v[212:215], 0
	v_mfma_f32_16x16x32_bf16 v[18:21], v[130:133], v[220:223], 0
	v_mfma_f32_16x16x32_bf16 v[10:13], v[138:141], v[220:223], 0
	v_mfma_f32_16x16x32_bf16 v[62:65], v[134:137], v[200:203], v[62:65]
	v_mfma_f32_16x16x32_bf16 v[58:61], v[142:145], v[200:203], v[58:61]
	v_mfma_f32_16x16x32_bf16 v[50:53], v[134:137], v[208:211], v[50:53]
	v_mfma_f32_16x16x32_bf16 v[42:45], v[142:145], v[208:211], v[42:45]
	v_mfma_f32_16x16x32_bf16 v[34:37], v[134:137], v[216:219], v[34:37]
	v_mfma_f32_16x16x32_bf16 v[26:29], v[142:145], v[216:219], v[26:29]
	v_mfma_f32_16x16x32_bf16 v[18:21], v[134:137], v[224:227], v[18:21]
	v_mfma_f32_16x16x32_bf16 v[10:13], v[142:145], v[224:227], v[10:13]
	s_setprio 0
	s_setprio 1
	v_mfma_f32_16x16x32_bf16 v[54:57], v[156:159], v[182:185], 0
	v_mfma_f32_16x16x32_bf16 v[46:49], v[172:175], v[182:185], 0
	v_mfma_f32_16x16x32_bf16 v[38:41], v[156:159], v[204:207], 0
	v_mfma_f32_16x16x32_bf16 v[30:33], v[172:175], v[204:207], 0
	v_mfma_f32_16x16x32_bf16 v[22:25], v[156:159], v[212:215], 0
	v_mfma_f32_16x16x32_bf16 v[14:17], v[172:175], v[212:215], 0
	v_mfma_f32_16x16x32_bf16 v[6:9], v[156:159], v[220:223], 0
	v_mfma_f32_16x16x32_bf16 v[2:5], v[172:175], v[220:223], 0
	v_mfma_f32_16x16x32_bf16 v[54:57], v[164:167], v[200:203], v[54:57]
	v_mfma_f32_16x16x32_bf16 v[46:49], v[178:181], v[200:203], v[46:49]
	v_mfma_f32_16x16x32_bf16 v[38:41], v[164:167], v[208:211], v[38:41]
	v_mfma_f32_16x16x32_bf16 v[30:33], v[178:181], v[208:211], v[30:33]
	v_mfma_f32_16x16x32_bf16 v[22:25], v[164:167], v[216:219], v[22:25]
	v_mfma_f32_16x16x32_bf16 v[14:17], v[178:181], v[216:219], v[14:17]
	v_mfma_f32_16x16x32_bf16 v[6:9], v[164:167], v[224:227], v[6:9]
	v_mfma_f32_16x16x32_bf16 v[2:5], v[178:181], v[224:227], v[2:5]
	s_setprio 0
	s_barrier
	s_add_i32 s40, 0, 0x18000
	s_add_i32 s41, 0, 0x1c000
	v_add_u32_e32 v142, s40, v161
	v_add_u32_e32 v177, s41, v161
	ds_read_b128 v[130:133], v142
	ds_read_b128 v[134:137], v142 offset:1024
	ds_read_b128 v[138:141], v142 offset:2048
	ds_read_b128 v[142:145], v142 offset:3072
	ds_read_b128 v[156:159], v177
	ds_read_b128 v[164:167], v177 offset:1024
	ds_read_b128 v[172:175], v177 offset:2048
	ds_read_b128 v[178:181], v177 offset:3072
	s_add_u32 s20, s20, 0x20000
	s_addc_u32 s21, s21, 0
	s_mov_b32 m0, s27
	v_lshl_add_u64 v[236:237], s[20:21], 0, v[150:151]
	ds_read_b128 v[182:185], v176 offset:32768
	ds_read_b128 v[200:203], v176 offset:33792
	ds_read_b128 v[204:207], v176 offset:34816
	ds_read_b128 v[208:211], v176 offset:35840
	ds_read_b128 v[212:215], v176 offset:36864
	ds_read_b128 v[216:219], v176 offset:37888
	ds_read_b128 v[220:223], v176 offset:38912
	ds_read_b128 v[224:227], v176 offset:39936
	global_load_lds_dwordx4 v[236:237], off
	v_lshl_add_u64 v[236:237], s[20:21], 0, v[148:149]
	s_mov_b32 m0, s28
	s_nop 0
	global_load_lds_dwordx4 v[236:237], off
	s_waitcnt vmcnt(8)
	s_waitcnt lgkmcnt(0)
	s_barrier
	s_setprio 1
	s_waitcnt lgkmcnt(0)
	v_mfma_f32_16x16x32_bf16 v[126:129], v[130:133], v[182:185], v[126:129]
	v_mfma_f32_16x16x32_bf16 v[122:125], v[138:141], v[182:185], v[122:125]
	v_mfma_f32_16x16x32_bf16 v[114:117], v[130:133], v[204:207], v[114:117]
	v_mfma_f32_16x16x32_bf16 v[106:109], v[138:141], v[204:207], v[106:109]
	v_mfma_f32_16x16x32_bf16 v[98:101], v[130:133], v[212:215], v[98:101]
	v_mfma_f32_16x16x32_bf16 v[90:93], v[138:141], v[212:215], v[90:93]
	v_mfma_f32_16x16x32_bf16 v[82:85], v[130:133], v[220:223], v[82:85]
	v_mfma_f32_16x16x32_bf16 v[74:77], v[138:141], v[220:223], v[74:77]
	v_mfma_f32_16x16x32_bf16 v[126:129], v[134:137], v[200:203], v[126:129]
	v_mfma_f32_16x16x32_bf16 v[122:125], v[142:145], v[200:203], v[122:125]
	v_mfma_f32_16x16x32_bf16 v[114:117], v[134:137], v[208:211], v[114:117]
	v_mfma_f32_16x16x32_bf16 v[106:109], v[142:145], v[208:211], v[106:109]
	v_mfma_f32_16x16x32_bf16 v[98:101], v[134:137], v[216:219], v[98:101]
	v_mfma_f32_16x16x32_bf16 v[90:93], v[142:145], v[216:219], v[90:93]
	v_mfma_f32_16x16x32_bf16 v[82:85], v[134:137], v[224:227], v[82:85]
	v_mfma_f32_16x16x32_bf16 v[74:77], v[142:145], v[224:227], v[74:77]
	s_setprio 0
	s_setprio 1
	v_mfma_f32_16x16x32_bf16 v[118:121], v[156:159], v[182:185], v[118:121]
	v_mfma_f32_16x16x32_bf16 v[110:113], v[172:175], v[182:185], v[110:113]
	v_mfma_f32_16x16x32_bf16 v[102:105], v[156:159], v[204:207], v[102:105]
	v_mfma_f32_16x16x32_bf16 v[94:97], v[172:175], v[204:207], v[94:97]
	v_mfma_f32_16x16x32_bf16 v[86:89], v[156:159], v[212:215], v[86:89]
	v_mfma_f32_16x16x32_bf16 v[78:81], v[172:175], v[212:215], v[78:81]
	v_mfma_f32_16x16x32_bf16 v[70:73], v[156:159], v[220:223], v[70:73]
	v_mfma_f32_16x16x32_bf16 v[66:69], v[172:175], v[220:223], v[66:69]
	v_mfma_f32_16x16x32_bf16 v[118:121], v[164:167], v[200:203], v[118:121]
	v_mfma_f32_16x16x32_bf16 v[110:113], v[178:181], v[200:203], v[110:113]
	v_mfma_f32_16x16x32_bf16 v[102:105], v[164:167], v[208:211], v[102:105]
	v_mfma_f32_16x16x32_bf16 v[94:97], v[178:181], v[208:211], v[94:97]
	v_mfma_f32_16x16x32_bf16 v[86:89], v[164:167], v[216:219], v[86:89]
	v_mfma_f32_16x16x32_bf16 v[78:81], v[178:181], v[216:219], v[78:81]
	v_mfma_f32_16x16x32_bf16 v[70:73], v[164:167], v[224:227], v[70:73]
	v_mfma_f32_16x16x32_bf16 v[66:69], v[178:181], v[224:227], v[66:69]
	s_setprio 0
	s_barrier
; #define PG8_STAGE(bufoff, gbase, voff) do { _Pragma("unroll") for (int _i = 0; _i < 2; ++_i) \
;         __builtin_amdgcn_global_load_lds((const unsigned*)((const char*)(gbase) + (voff)[_i]), (PG8_LAS unsigned*)(lds + (bufoff) + ldsw + _i * 8192), 16, 0, 0); } while (0)
; #define PG8_LDA(dst, b, h) do { _Pragma("unroll") for (int m = 0; m < 4; ++m) _Pragma("unroll") for (int k = 0; k < 2; ++k) dst[m][k] = *(const PG8_LAS bf16x8*)(lds + PG8_SA(b, h) + aoff + m * 2048 + k * 1024); } while (0)
; #define PG8_LDB(dst, b, h) do { _Pragma("unroll") for (int n = 0; n < 2; ++n) _Pragma("unroll") for (int k = 0; k < 2; ++k) dst[n][k] = *(const PG8_LAS bf16x8*)(lds + PG8_SB(b, h) + boff + n * 2048 + k * 1024); } while (0)
; template <class Epi, class Sched, bool ALIGN_EPI = false, bool SP2 = false>
; __device__ __forceinline__ void gemm_phase(PG8_LAS unsigned char* lds, const Gemm g, const Sched& S, const Epi& E) {
;     ...
;         for (int t = 0; t < nt; t += 2) {
;             const bool last = (t == nt - 2);
;             const char* a1 = cA + (size_t)(t + 1) * kstep;
;             const char* a2 = last ? nA : cA + (size_t)(t + 2) * kstep; const char* b2 = last ? nB : cB + (size_t)(t + 2) * kstep;
;             const char* a3 = a2 + kstep; const char* b3 = b2 + kstep;
;             if (last && has_next) S.a_ready(nxt);
;             if constexpr (SP2) {
;             PG8_LDB(B0, 0, 0); PG8_LDB(B1, 0, 1); PG8_SCHED; PG8_LDA(At, 0, 0); PG8_STAGE(PG8_SA(1, 1), a1 + hstep, voffA);
;             PG8_WAIT_V(8); PG8_WAIT_L(0); PG8_BAR; PG8_MMA(0, 0, At, B0); PG8_MMA(0, 1, At, B1); PG8_BAR; PG8_SCHED;
;             PG8_LDA(At, 0, 1); PG8_STAGE(PG8_SB(0, 0), b2, voffB); PG8_STAGE(PG8_SB(0, 1), b2 + hstep, voffB); PG8_STAGE(PG8_SA(0, 0), a2, voffA);
;             PG8_WAIT_V(8); PG8_WAIT_L(0); PG8_BAR; PG8_MMA(1, 0, At, B0); PG8_MMA(1, 1, At, B1); PG8_BAR; PG8_SCHED;
;             PG8_LDB(B0, 1, 0); PG8_LDB(B1, 1, 1); PG8_SCHED; PG8_LDA(At, 1, 0); PG8_STAGE(PG8_SA(0, 1), a2 + hstep, voffA);
;             PG8_WAIT_V(8); PG8_WAIT_L(0); PG8_BAR; PG8_MMA(0, 0, At, B0); PG8_MMA(0, 1, At, B1); PG8_BAR; PG8_SCHED;
;             PG8_LDA(At, 1, 1); PG8_STAGE(PG8_SB(1, 0), b3, voffB); PG8_STAGE(PG8_SB(1, 1), b3 + hstep, voffB); PG8_STAGE(PG8_SA(1, 0), a3, voffA);
;             PG8_WAIT_V(8); PG8_WAIT_L(0); PG8_BAR; PG8_MMA(1, 0, At, B0); PG8_MMA(1, 1, At, B1); PG8_BAR; PG8_SCHED;
	s_add_i32 s20, s40, s22
	v_lshl_add_u64 v[228:229], v[228:229], 0, s[44:45]
	s_mov_b32 m0, s20
	ds_read_b128 v[182:185], v176 offset:49152
	ds_read_b128 v[200:203], v176 offset:50176
	ds_read_b128 v[204:207], v176 offset:51200
	ds_read_b128 v[208:211], v176 offset:52224
	ds_read_b128 v[212:215], v176 offset:53248
	ds_read_b128 v[216:219], v176 offset:54272
	ds_read_b128 v[220:223], v176 offset:55296
	ds_read_b128 v[224:227], v176 offset:56320
	global_load_lds_dwordx4 v[228:229], off
	s_add_i32 m0, s20, 0x2000
	s_add_u32 s18, s18, 0x20080
	v_lshl_add_u64 v[228:229], v[230:231], 0, s[44:45]
	s_addc_u32 s19, s19, 0
	s_add_i32 s20, s41, s22
	global_load_lds_dwordx4 v[228:229], off
	v_lshl_add_u64 v[228:229], s[18:19], 0, v[0:1]
	s_mov_b32 m0, s20
	s_nop 0
	global_load_lds_dwordx4 v[228:229], off
	v_lshl_add_u64 v[228:229], s[18:19], 0, v[146:147]
	s_add_i32 m0, s20, 0x2000
	s_nop 0
	global_load_lds_dwordx4 v[228:229], off
	v_lshl_add_u64 v[228:229], v[232:233], 0, s[44:45]
	s_mov_b32 m0, s29
	s_nop 0
	global_load_lds_dwordx4 v[228:229], off
	v_lshl_add_u64 v[228:229], v[234:235], 0, s[44:45]
	s_mov_b32 m0, s30
	s_nop 0
	global_load_lds_dwordx4 v[228:229], off
	s_waitcnt vmcnt(8)
	s_waitcnt lgkmcnt(0)
	s_barrier
	s_setprio 1
	s_waitcnt lgkmcnt(0)
	v_mfma_f32_16x16x32_bf16 v[62:65], v[130:133], v[182:185], v[62:65]
	v_mfma_f32_16x16x32_bf16 v[58:61], v[138:141], v[182:185], v[58:61]
	v_mfma_f32_16x16x32_bf16 v[50:53], v[130:133], v[204:207], v[50:53]
	v_mfma_f32_16x16x32_bf16 v[42:45], v[138:141], v[204:207], v[42:45]
	v_mfma_f32_16x16x32_bf16 v[34:37], v[130:133], v[212:215], v[34:37]
	v_mfma_f32_16x16x32_bf16 v[26:29], v[138:141], v[212:215], v[26:29]
	v_mfma_f32_16x16x32_bf16 v[18:21], v[130:133], v[220:223], v[18:21]
	v_mfma_f32_16x16x32_bf16 v[10:13], v[138:141], v[220:223], v[10:13]
	v_mfma_f32_16x16x32_bf16 v[62:65], v[134:137], v[200:203], v[62:65]
	v_mfma_f32_16x16x32_bf16 v[58:61], v[142:145], v[200:203], v[58:61]
	v_mfma_f32_16x16x32_bf16 v[50:53], v[134:137], v[208:211], v[50:53]
	v_mfma_f32_16x16x32_bf16 v[42:45], v[142:145], v[208:211], v[42:45]
	v_mfma_f32_16x16x32_bf16 v[34:37], v[134:137], v[216:219], v[34:37]
	v_mfma_f32_16x16x32_bf16 v[26:29], v[142:145], v[216:219], v[26:29]
	v_mfma_f32_16x16x32_bf16 v[18:21], v[134:137], v[224:227], v[18:21]
	v_mfma_f32_16x16x32_bf16 v[10:13], v[142:145], v[224:227], v[10:13]
	s_setprio 0
	s_setprio 1
	v_mfma_f32_16x16x32_bf16 v[54:57], v[156:159], v[182:185], v[54:57]
	v_mfma_f32_16x16x32_bf16 v[46:49], v[172:175], v[182:185], v[46:49]
	v_mfma_f32_16x16x32_bf16 v[38:41], v[156:159], v[204:207], v[38:41]
	v_mfma_f32_16x16x32_bf16 v[30:33], v[172:175], v[204:207], v[30:33]
	v_mfma_f32_16x16x32_bf16 v[22:25], v[156:159], v[212:215], v[22:25]
	v_mfma_f32_16x16x32_bf16 v[14:17], v[172:175], v[212:215], v[14:17]
	v_mfma_f32_16x16x32_bf16 v[6:9], v[156:159], v[220:223], v[6:9]
	v_mfma_f32_16x16x32_bf16 v[2:5], v[172:175], v[220:223], v[2:5]
	v_mfma_f32_16x16x32_bf16 v[54:57], v[164:167], v[200:203], v[54:57]
	v_mfma_f32_16x16x32_bf16 v[46:49], v[178:181], v[200:203], v[46:49]
	v_mfma_f32_16x16x32_bf16 v[38:41], v[164:167], v[208:211], v[38:41]
	v_mfma_f32_16x16x32_bf16 v[30:33], v[178:181], v[208:211], v[30:33]
	v_mfma_f32_16x16x32_bf16 v[22:25], v[164:167], v[216:219], v[22:25]
	v_mfma_f32_16x16x32_bf16 v[14:17], v[178:181], v[216:219], v[14:17]
	v_mfma_f32_16x16x32_bf16 v[6:9], v[164:167], v[224:227], v[6:9]
	v_mfma_f32_16x16x32_bf16 v[2:5], v[178:181], v[224:227], v[2:5]
	s_setprio 0
	s_barrier
	s_add_i32 s39, s39, 2
	s_add_u32 s0, s0, 0x100
	s_addc_u32 s1, s1, 0
	s_add_u32 s37, s37, 0x100
	s_addc_u32 s38, s38, 0
	s_cmp_gt_u32 s39, 5
